# mLSTM chunk output: the two 1/den divisions as v_rcp_f32 (on top of v173)
# speedup vs baseline: 1.0005x; 1.0005x over previous
; DI unsigned pack2(float a, float b) { f32x2_t v = {a, b}; bf16x2_t r = __builtin_convertvector(v, bf16x2_t); return __builtin_bit_cast(unsigned, r); }
; DI void mlstm_job(const PX& p, int l, int job, unsigned char* smem) {
;     ...
;       if (w < 6) {
; #pragma unroll
;         for (int ti = 0; ti < 2; ti++) {
;           const int tl = ti * 32 + lr;
;           const float dn = fmaxf(fabsf(denA[tl]), emtA[par * 64 + tl]);
;           const float inv = 1.f / dn;
;           const int pos = c * 64 + tl;
;           const int t = dir ? Lseg - 1 - pos : pos;
;           bfu* dst = H + (size_t)(tokbase + t) * 768 + h * 192 + 32 * w + 4 * lh;
; #pragma unroll
;           for (int g4 = 0; g4 < 4; g4++) {
;             uint2 o;
;             o.x = pack2(num[ti][4 * g4] * inv, num[ti][4 * g4 + 1] * inv);
;             o.y = pack2(num[ti][4 * g4 + 2] * inv, num[ti][4 * g4 + 3] * inv);
;             *(uint2*)(dst + 8 * g4) = o;
;           }
;         }
;       }
.LBB0_462:
	s_or_b64 exec, exec, s[62:63]
	s_barrier
	s_mov_b64 s[62:63], exec
	v_readlane_b32 s0, v255, 27
	v_readlane_b32 s1, v255, 28
	s_and_b64 s[0:1], s[62:63], s[0:1]
	s_mov_b64 exec, s[0:1]
	s_cbranch_execz .LBB0_448
	v_add_u32_e32 v2, s27, v251
	ds_read_b32 v0, v189
	ds_read2_b32 v[2:3], v2 offset1:32
	s_waitcnt lgkmcnt(1)
	v_max_f32_e64 v0, |v0|, |v0|
	s_waitcnt lgkmcnt(0)
	v_max_f32_e32 v2, v2, v2
	v_max_f32_e32 v0, v0, v2
	v_rcp_f32_e32 v0, v0
	s_nop 0
	v_or_b32_e32 v2, s26, v176
	v_xad_u32 v4, v2, -1, s69
	v_cndmask_b32_e64 v2, v4, v2, s[4:5]
	v_add_u32_e32 v2, s61, v2
	v_mad_i64_i32 v[4:5], s[0:1], v2, s81, v[166:167]
	v_and_b32_e32 v14, 32, v211
	v_lshrrev_b32_e32 v14, 2, v14
	v_mov_b32_e32 v15, 0
	v_lshl_add_u64 v[4:5], v[4:5], 0, v[14:15]
	v_pk_mul_f32 v[6:7], v[128:129], v[0:1] op_sel_hi:[1,0]
	v_pk_mul_f32 v[8:9], v[130:131], v[0:1] op_sel_hi:[1,0]
	v_pk_mul_f32 v[10:11], v[132:133], v[0:1] op_sel_hi:[1,0]
	v_pk_mul_f32 v[12:13], v[134:135], v[0:1] op_sel_hi:[1,0]
	s_nop 0
	v_cvt_pk_bf16_f32 v6, v6, v7
	v_cvt_pk_bf16_f32 v7, v8, v9
	v_cvt_pk_bf16_f32 v8, v10, v11
	v_cvt_pk_bf16_f32 v9, v12, v13
	s_nop 1
	v_permlane32_swap_b32_e32 v6, v8
	v_permlane32_swap_b32_e32 v7, v9
	global_store_dwordx4 v[4:5], v[6:9], off
	s_nop 1
	v_pk_mul_f32 v[6:7], v[136:137], v[0:1] op_sel_hi:[1,0]
	v_pk_mul_f32 v[8:9], v[138:139], v[0:1] op_sel_hi:[1,0]
	v_pk_mul_f32 v[10:11], v[140:141], v[0:1] op_sel_hi:[1,0]
	v_pk_mul_f32 v[12:13], v[142:143], v[0:1] op_sel_hi:[1,0]
	s_nop 0
	v_cvt_pk_bf16_f32 v6, v6, v7
	v_cvt_pk_bf16_f32 v7, v8, v9
	v_cvt_pk_bf16_f32 v8, v10, v11
	v_cvt_pk_bf16_f32 v9, v12, v13
	s_nop 1
	v_permlane32_swap_b32_e32 v6, v8
	v_permlane32_swap_b32_e32 v7, v9
	global_store_dwordx4 v[4:5], v[6:9], off offset:32
	s_nop 1
	ds_read_b32 v0, v250
	v_max_f32_e32 v2, v3, v3
	s_waitcnt lgkmcnt(0)
	v_max_f32_e64 v0, |v0|, |v0|
	v_max_f32_e32 v0, v0, v2
	v_rcp_f32_e32 v0, v0
	s_nop 0
	v_or_b32_e32 v2, s26, v249
	v_xad_u32 v4, v2, -1, s69
	v_cndmask_b32_e64 v2, v4, v2, s[4:5]
	v_add_u32_e32 v2, s61, v2
	v_mad_i64_i32 v[4:5], s[0:1], v2, s81, v[166:167]
	v_and_b32_e32 v14, 32, v211
	v_lshrrev_b32_e32 v14, 2, v14
	v_mov_b32_e32 v15, 0
	v_lshl_add_u64 v[4:5], v[4:5], 0, v[14:15]
	v_pk_mul_f32 v[6:7], v[112:113], v[0:1] op_sel_hi:[1,0]
	v_pk_mul_f32 v[8:9], v[114:115], v[0:1] op_sel_hi:[1,0]
	v_pk_mul_f32 v[10:11], v[116:117], v[0:1] op_sel_hi:[1,0]
	v_pk_mul_f32 v[12:13], v[118:119], v[0:1] op_sel_hi:[1,0]
	s_nop 0
	v_cvt_pk_bf16_f32 v6, v6, v7
	v_cvt_pk_bf16_f32 v7, v8, v9
	v_cvt_pk_bf16_f32 v8, v10, v11
	v_cvt_pk_bf16_f32 v9, v12, v13
	s_nop 1
	v_permlane32_swap_b32_e32 v6, v8
	v_permlane32_swap_b32_e32 v7, v9
	global_store_dwordx4 v[4:5], v[6:9], off
	s_nop 1
	v_pk_mul_f32 v[6:7], v[120:121], v[0:1] op_sel_hi:[1,0]
	v_pk_mul_f32 v[8:9], v[122:123], v[0:1] op_sel_hi:[1,0]
	v_pk_mul_f32 v[10:11], v[124:125], v[0:1] op_sel_hi:[1,0]
	v_pk_mul_f32 v[12:13], v[126:127], v[0:1] op_sel_hi:[1,0]
	s_nop 0
	v_cvt_pk_bf16_f32 v6, v6, v7
	v_cvt_pk_bf16_f32 v7, v8, v9
	v_cvt_pk_bf16_f32 v8, v10, v11
	v_cvt_pk_bf16_f32 v9, v12, v13
	s_nop 1
	v_permlane32_swap_b32_e32 v6, v8
	v_permlane32_swap_b32_e32 v7, v9
	global_store_dwordx4 v[4:5], v[6:9], off offset:32
	s_nop 1
	s_branch .LBB0_448
